# nt hint also on the SSD state-scan's once-read STATES/CDEC loads (P3), on top of P0/P3 weight streams and w_o-epilogue x loads
# baseline (speedup 1.0000x reference)
; __device__ __forceinline__ unsigned cvt_pk_bf16(float lo, float hi) { unsigned r; asm volatile("v_cvt_pk_bf16_f32 %0, %1, %2" : "=v"(r) : "v"(lo), "v"(hi)); return r; }
; __device__ __forceinline__ void ssd_scan(const float* __restrict__ STATES, const float* __restrict__ CDEC, bf16_t* __restrict__ PREV, size_t gt, size_t NGT) {
;     ...
;     for (size_t e = gt; e < (size_t)NSH * 64 * 128 / 2; e += NGT) {
;         const int hd = (int)(e >> 12);
;         f32x2 s = {0.f, 0.f};
;         for (int cb = 0; cb < 128; cb += 16) {
;             f32x2 v[16]; float d[16];
; #pragma unroll
;             for (int k = 0; k < 16; ++k) { const unsigned w = ((const unsigned*)STATES + (size_t)(cb + k) * NSH * 64 * 64)[e]; v[k][0] = __uint_as_float(w << 16); v[k][1] = __uint_as_float(w & 0xffff0000u); d[k] = CDEC[(cb + k) * 32 + hd]; }
; #pragma unroll
;             for (int k = 0; k < 16; ++k) { ((unsigned*)(PREV + (size_t)(cb + k) * NSH * 64 * 128))[e] = cvt_pk_bf16(s[0], s[1]); s = s * d[k] + v[k]; }
.LBB0_752:
	v_add_co_u32_e32 v14, vcc, 0xe6880000, v10
	v_add_u32_e32 v6, 0xfffffe20, v8
	s_nop 0
	v_addc_co_u32_e32 v15, vcc, -1, v11, vcc
	global_load_dword v1, v[14:15], off nt
	v_add_co_u32_e32 v14, vcc, 0xe6900000, v10
	v_lshl_add_u64 v[16:17], v[6:7], 2, s[10:11]
	s_nop 0
	v_addc_co_u32_e32 v15, vcc, -1, v11, vcc
	global_load_dword v9, v[14:15], off nt
	v_add_co_u32_e32 v14, vcc, 0xe6980000, v10
	global_load_dword v16, v[16:17], off nt
	s_nop 0
	v_addc_co_u32_e32 v15, vcc, -1, v11, vcc
	global_load_dword v23, v[14:15], off nt
	v_add_co_u32_e32 v14, vcc, 0xe6a00000, v10
	v_add_u32_e32 v6, 0xfffffe40, v8
	s_nop 0
	v_addc_co_u32_e32 v15, vcc, -1, v11, vcc
	global_load_dword v27, v[14:15], off nt
	v_add_co_u32_e32 v14, vcc, 0xe6a80000, v10
	v_lshl_add_u64 v[20:21], v[6:7], 2, s[10:11]
	s_nop 0
	v_addc_co_u32_e32 v15, vcc, -1, v11, vcc
	global_load_dword v31, v[14:15], off nt
	v_add_co_u32_e32 v14, vcc, 0xe6b00000, v10
	global_load_dword v20, v[20:21], off nt
	s_nop 0
	v_addc_co_u32_e32 v15, vcc, -1, v11, vcc
	global_load_dword v35, v[14:15], off nt
	v_add_co_u32_e32 v14, vcc, 0xe6b80000, v10
	v_add_u32_e32 v6, 0xfffffe60, v8
	s_nop 0
	v_addc_co_u32_e32 v15, vcc, -1, v11, vcc
	global_load_dword v39, v[14:15], off nt
	v_add_co_u32_e32 v14, vcc, 0xe6c00000, v10
	v_lshl_add_u64 v[24:25], v[6:7], 2, s[10:11]
	s_nop 0
	v_addc_co_u32_e32 v15, vcc, -1, v11, vcc
	global_load_dword v43, v[14:15], off nt
	v_add_co_u32_e32 v14, vcc, 0xe6c80000, v10
	global_load_dword v24, v[24:25], off nt
	s_nop 0
	v_addc_co_u32_e32 v15, vcc, -1, v11, vcc
	global_load_dword v47, v[14:15], off nt
	v_add_co_u32_e32 v14, vcc, 0xe6d00000, v10
	v_add_u32_e32 v6, 0xfffffe80, v8
	s_nop 0
	v_addc_co_u32_e32 v15, vcc, -1, v11, vcc
	global_load_dword v51, v[14:15], off nt
	v_add_co_u32_e32 v14, vcc, 0xe6d80000, v10
	v_lshl_add_u64 v[28:29], v[6:7], 2, s[10:11]
	s_nop 0
	v_addc_co_u32_e32 v15, vcc, -1, v11, vcc
	global_load_dword v55, v[14:15], off nt
	v_add_co_u32_e32 v14, vcc, 0xe6e00000, v10
	global_load_dword v28, v[28:29], off nt
	s_nop 0
	v_addc_co_u32_e32 v15, vcc, -1, v11, vcc
	global_load_dword v59, v[14:15], off nt
	v_add_co_u32_e32 v14, vcc, 0xe6e80000, v10
	v_add_u32_e32 v6, 0xfffffea0, v8
	s_nop 0
	v_addc_co_u32_e32 v15, vcc, -1, v11, vcc
	global_load_dword v63, v[14:15], off nt
	v_add_co_u32_e32 v14, vcc, 0xe6f00000, v10
	v_lshl_add_u64 v[32:33], v[6:7], 2, s[10:11]
	s_nop 0
	v_addc_co_u32_e32 v15, vcc, -1, v11, vcc
	global_load_dword v67, v[14:15], off nt
	v_add_co_u32_e32 v14, vcc, 0xe6f80000, v10
	global_load_dword v32, v[32:33], off nt
	s_nop 0
	v_addc_co_u32_e32 v15, vcc, -1, v11, vcc
	global_load_dword v71, v[14:15], off nt
	v_add_co_u32_e32 v14, vcc, 0xe7000000, v10
	v_add_u32_e32 v6, 0xfffffec0, v8
	s_nop 0
	v_addc_co_u32_e32 v15, vcc, -1, v11, vcc
	global_load_dword v76, v[14:15], off nt
	v_lshl_add_u64 v[36:37], v[6:7], 2, s[10:11]
	global_load_dword v36, v[36:37], off nt
	v_add_u32_e32 v6, 0xfffffee0, v8
	v_lshl_add_u64 v[40:41], v[6:7], 2, s[10:11]
	global_load_dword v40, v[40:41], off nt
	v_add_u32_e32 v6, 0xffffff00, v8
	v_lshl_add_u64 v[44:45], v[6:7], 2, s[10:11]
	global_load_dword v44, v[44:45], off nt
	v_add_u32_e32 v6, 0xffffff20, v8
	v_lshl_add_u64 v[48:49], v[6:7], 2, s[10:11]
	global_load_dword v48, v[48:49], off nt
	v_add_u32_e32 v6, 0xffffff40, v8
	v_lshl_add_u64 v[52:53], v[6:7], 2, s[10:11]
	global_load_dword v52, v[52:53], off nt
	v_add_u32_e32 v6, 0xffffff60, v8
	v_lshl_add_u64 v[56:57], v[6:7], 2, s[10:11]
	global_load_dword v56, v[56:57], off nt
	v_add_u32_e32 v6, 0xffffff80, v8
	v_lshl_add_u64 v[60:61], v[6:7], 2, s[10:11]
	v_add_u32_e32 v6, 0xffffffa0, v8
	global_load_dword v60, v[60:61], off nt
	v_lshl_add_u64 v[64:65], v[6:7], 2, s[10:11]
	v_subrev_u32_e32 v6, 64, v8
	global_load_dword v64, v[64:65], off nt
	v_lshl_add_u64 v[68:69], v[6:7], 2, s[10:11]
	v_subrev_u32_e32 v6, 32, v8
	s_waitcnt vmcnt(0)
; __device__ __forceinline__ unsigned cvt_pk_bf16(float lo, float hi) { unsigned r; asm volatile("v_cvt_pk_bf16_f32 %0, %1, %2" : "=v"(r) : "v"(lo), "v"(hi)); return r; }
; __device__ __forceinline__ void ssd_scan(const float* __restrict__ STATES, const float* __restrict__ CDEC, bf16_t* __restrict__ PREV, size_t gt, size_t NGT) {
;     ...
;             for (int k = 0; k < 16; ++k) { const unsigned w = ((const unsigned*)STATES + (size_t)(cb + k) * NSH * 64 * 64)[e]; v[k][0] = __uint_as_float(w << 16); v[k][1] = __uint_as_float(w & 0xffff0000u); d[k] = CDEC[(cb + k) * 32 + hd]; }
; #pragma unroll
;             for (int k = 0; k < 16; ++k) { ((unsigned*)(PREV + (size_t)(cb + k) * NSH * 64 * 128))[e] = cvt_pk_bf16(s[0], s[1]); s = s * d[k] + v[k]; }
	v_lshlrev_b32_e32 v18, 16, v9
	v_and_b32_e32 v19, 0xffff0000, v9
	global_load_dword v68, v[68:69], off
	v_lshl_add_u64 v[74:75], v[6:7], 2, s[10:11]
	v_mov_b32_e32 v9, v7
	global_load_dword v6, v[74:75], off
	v_add_co_u32_e32 v78, vcc, 0xff880000, v10
	v_lshlrev_b32_e32 v14, 16, v1
	v_and_b32_e32 v15, 0xffff0000, v1
	v_addc_co_u32_e32 v79, vcc, -1, v11, vcc
	v_lshlrev_b32_e32 v22, 16, v23
	v_and_b32_e32 v23, 0xffff0000, v23
	v_lshlrev_b32_e32 v26, 16, v27
	v_and_b32_e32 v27, 0xffff0000, v27
	v_lshlrev_b32_e32 v30, 16, v31
	v_and_b32_e32 v31, 0xffff0000, v31
	v_lshlrev_b32_e32 v34, 16, v35
	v_and_b32_e32 v35, 0xffff0000, v35
	v_lshlrev_b32_e32 v38, 16, v39
	v_and_b32_e32 v39, 0xffff0000, v39
	v_lshlrev_b32_e32 v42, 16, v43
	v_and_b32_e32 v43, 0xffff0000, v43
	v_lshlrev_b32_e32 v46, 16, v47
	v_and_b32_e32 v47, 0xffff0000, v47
	v_lshlrev_b32_e32 v50, 16, v51
	v_and_b32_e32 v51, 0xffff0000, v51
	v_lshlrev_b32_e32 v54, 16, v55
	v_and_b32_e32 v55, 0xffff0000, v55
	v_lshlrev_b32_e32 v58, 16, v59
	v_and_b32_e32 v59, 0xffff0000, v59
	s_add_i32 s3, s3, 16
	s_cmpk_gt_u32 s3, 0x6f
	v_lshlrev_b32_e32 v62, 16, v63
	v_and_b32_e32 v63, 0xffff0000, v63
	v_lshlrev_b32_e32 v66, 16, v67
	v_and_b32_e32 v67, 0xffff0000, v67
	v_lshlrev_b32_e32 v72, 16, v71
	v_and_b32_e32 v73, 0xffff0000, v71
	v_lshlrev_b32_e32 v74, 16, v76
	v_and_b32_e32 v75, 0xffff0000, v76
	v_lshl_add_u64 v[76:77], v[8:9], 2, s[10:11]
	global_load_dword v76, v[76:77], off
	v_cvt_pk_bf16_f32 v1, v12, v13
	v_pk_fma_f32 v[12:13], v[12:13], v[16:17], v[14:15] op_sel_hi:[1,0,1]
	v_add_co_u32_e32 v14, vcc, 0xff900000, v10
	global_store_dword v[78:79], v1, off
	s_nop 0
	v_addc_co_u32_e32 v15, vcc, -1, v11, vcc
	v_cvt_pk_bf16_f32 v1, v12, v13
	global_store_dword v[14:15], v1, off
	v_add_co_u32_e32 v14, vcc, 0xff980000, v10
	v_pk_fma_f32 v[12:13], v[12:13], v[20:21], v[18:19] op_sel_hi:[1,0,1]
	s_nop 0
	v_addc_co_u32_e32 v15, vcc, -1, v11, vcc
	v_cvt_pk_bf16_f32 v1, v12, v13
	global_store_dword v[14:15], v1, off
	v_add_co_u32_e32 v14, vcc, 0xffa00000, v10
	v_pk_fma_f32 v[12:13], v[12:13], v[24:25], v[22:23] op_sel_hi:[1,0,1]
	s_nop 0
	v_addc_co_u32_e32 v15, vcc, -1, v11, vcc
	v_cvt_pk_bf16_f32 v1, v12, v13
	global_store_dword v[14:15], v1, off
	v_add_co_u32_e32 v14, vcc, 0xffa80000, v10
	v_pk_fma_f32 v[12:13], v[12:13], v[28:29], v[26:27] op_sel_hi:[1,0,1]
	s_nop 0
	v_addc_co_u32_e32 v15, vcc, -1, v11, vcc
	v_cvt_pk_bf16_f32 v1, v12, v13
	global_store_dword v[14:15], v1, off
	v_add_co_u32_e32 v14, vcc, 0xffb00000, v10
	v_pk_fma_f32 v[12:13], v[12:13], v[32:33], v[30:31] op_sel_hi:[1,0,1]
	s_nop 0
	v_addc_co_u32_e32 v15, vcc, -1, v11, vcc
	v_cvt_pk_bf16_f32 v1, v12, v13
	global_store_dword v[14:15], v1, off
	v_add_co_u32_e32 v14, vcc, 0xffb80000, v10
	v_pk_fma_f32 v[12:13], v[12:13], v[36:37], v[34:35] op_sel_hi:[1,0,1]
	s_nop 0
	v_addc_co_u32_e32 v15, vcc, -1, v11, vcc
	v_cvt_pk_bf16_f32 v1, v12, v13
	global_store_dword v[14:15], v1, off
	v_add_co_u32_e32 v14, vcc, 0xffc00000, v10
	v_pk_fma_f32 v[12:13], v[12:13], v[40:41], v[38:39] op_sel_hi:[1,0,1]
	s_nop 0
	v_addc_co_u32_e32 v15, vcc, -1, v11, vcc
	v_cvt_pk_bf16_f32 v1, v12, v13
	global_store_dword v[14:15], v1, off
	v_add_co_u32_e32 v14, vcc, 0xffc80000, v10
	v_pk_fma_f32 v[12:13], v[12:13], v[44:45], v[42:43] op_sel_hi:[1,0,1]
	s_nop 0
	v_addc_co_u32_e32 v15, vcc, -1, v11, vcc
	v_cvt_pk_bf16_f32 v1, v12, v13
	global_store_dword v[14:15], v1, off
	v_add_co_u32_e32 v14, vcc, 0xffd00000, v10
	v_pk_fma_f32 v[12:13], v[12:13], v[48:49], v[46:47] op_sel_hi:[1,0,1]
	s_nop 0
	v_addc_co_u32_e32 v15, vcc, -1, v11, vcc
	v_cvt_pk_bf16_f32 v1, v12, v13
	global_store_dword v[14:15], v1, off
	v_add_co_u32_e32 v14, vcc, 0xffd80000, v10
	v_pk_fma_f32 v[12:13], v[12:13], v[52:53], v[50:51] op_sel_hi:[1,0,1]
	s_nop 0
	v_addc_co_u32_e32 v15, vcc, -1, v11, vcc
	v_cvt_pk_bf16_f32 v1, v12, v13
	global_store_dword v[14:15], v1, off
	v_add_co_u32_e32 v14, vcc, 0xffe00000, v10
	v_pk_fma_f32 v[12:13], v[12:13], v[56:57], v[54:55] op_sel_hi:[1,0,1]
	s_nop 0
	v_addc_co_u32_e32 v15, vcc, -1, v11, vcc
	v_cvt_pk_bf16_f32 v1, v12, v13
	global_store_dword v[14:15], v1, off
	v_add_co_u32_e32 v14, vcc, 0xffe80000, v10
	v_pk_fma_f32 v[12:13], v[12:13], v[60:61], v[58:59] op_sel_hi:[1,0,1]
	s_nop 0
	v_addc_co_u32_e32 v15, vcc, -1, v11, vcc
	v_cvt_pk_bf16_f32 v1, v12, v13
	global_store_dword v[14:15], v1, off
	v_add_co_u32_e32 v14, vcc, 0xfff00000, v10
	v_pk_fma_f32 v[12:13], v[12:13], v[64:65], v[62:63] op_sel_hi:[1,0,1]
	s_nop 0
	v_addc_co_u32_e32 v15, vcc, -1, v11, vcc
	v_cvt_pk_bf16_f32 v1, v12, v13
	global_store_dword v[14:15], v1, off
	s_waitcnt vmcnt(16)
	v_pk_fma_f32 v[12:13], v[12:13], v[68:69], v[66:67] op_sel_hi:[1,0,1]
	v_add_co_u32_e32 v14, vcc, 0xfff80000, v10
	v_cvt_pk_bf16_f32 v1, v12, v13
	s_waitcnt vmcnt(15)
	v_pk_fma_f32 v[12:13], v[12:13], v[6:7], v[72:73] op_sel_hi:[1,0,1]
	v_addc_co_u32_e32 v15, vcc, -1, v11, vcc
	global_store_dword v[14:15], v1, off
	v_cvt_pk_bf16_f32 v1, v12, v13
	global_store_dword v[10:11], v1, off
	s_waitcnt vmcnt(16)
	v_pk_fma_f32 v[12:13], v[12:13], v[76:77], v[74:75] op_sel_hi:[1,0,1]
	v_lshl_add_u64 v[10:11], v[10:11], 0, s[18:19]
	v_add_u32_e32 v8, 0x200, v8
	s_cbranch_scc0 .LBB0_752
	v_lshl_add_u64 v[2:3], v[2:3], 0, s[8:9]
	v_cmp_lt_u64_e32 vcc, s[24:25], v[2:3]
	s_or_b64 s[16:17], vcc, s[16:17]
	v_lshl_add_u64 v[4:5], v[4:5], 0, s[12:13]
	s_andn2_b64 exec, exec, s[16:17]
	s_cbranch_execnz .LBB0_751
